# first norm phase: the eight f32 row pieces are issued together (was three groups with waits in between)
# baseline (speedup 1.0000x reference)
; __device__ __forceinline__ unsigned pk2(float lo, float hi) { return f2bf(lo) | (f2bf(hi) << 16); }
; #define c opq(blockIdx.x)
; __device__ __forceinline__ void phase_norm_mod(const float* srcL, const float* srcC, const float* g, const float* mod_sh, const float* mod_sc, bf16_t* dst, int nrows, const float* part = nullptr, const float* pgate = nullptr, const bf16_t* srcLb = nullptr) {
;     ...
;         const bool isc = row >= NLAT; const float* src = isc ? srcC + (size_t)(row - NLAT) * DM : srcL + (size_t)row * DM; const int ridx = isc ? 4 : (row >> 12);
;         f32x4 v[8]; float s = 0.f;
; #pragma unroll
;         for (int j = 0; j < 8; ++j) {
;             if (srcLb != nullptr && !isc) { const unsigned long long w = *(const unsigned long long*)(srcLb + (size_t)row * DM + j * 256 + lane * 4); const unsigned lo = (unsigned)w, hi = (unsigned)(w >> 32);
;                 v[j] = (f32x4){__uint_as_float(lo << 16), __uint_as_float(lo & 0xffff0000u), __uint_as_float(hi << 16), __uint_as_float(hi & 0xffff0000u)}; }
;             else if (srcLb == nullptr && !isc) v[j] = __builtin_nontemporal_load((const f32x4*)(src + j * 256 + lane * 4));
;             else v[j] = *(const f32x4*)(src + j * 256 + lane * 4);
;             if (part != nullptr && isc) { const size_t po = (size_t)(row - NLAT) * DM + j * 256 + lane * 4; f32x4 ps = *(const f32x4*)(part + po);
; #pragma unroll
;                 for (int p = 1; p < 8; ++p) ps = ps + *(const f32x4*)(part + (size_t)p * (1024 * 2048) + po);
;                 v[j] = v[j] + ps * *(const f32x4*)(pgate + 4 * 12288 + j * 256 + lane * 4); }
;             s += (v[j].x * v[j].x + v[j].y * v[j].y) + (v[j].z * v[j].z + v[j].w * v[j].w); }
;         const float rstd = rsqrtf(wave_sum(s) * (1.f / DM) + 1e-6f);
;         const float* sh = mod_sh + (size_t)ridx * 12288; const float* sc = mod_sc + (size_t)ridx * 12288;
; #pragma unroll
;         for (int j = 0; j < 8; ++j) { const int c = j * 256 + lane * 4; const f32x4 gv = *(const f32x4*)(g + c), shv = *(const f32x4*)(sh + c), scv = *(const f32x4*)(sc + c);
;             const f32x4 y = (v[j] * rstd) * gv; const f32x4 h = y * (scv + 1.f) + shv;
;             u32x2 o; o.x = pk2(h.x, h.y); o.y = pk2(h.z, h.w); *(u32x2*)(dst + (size_t)row * DM + c) = o; }
.LBB0_137:
	s_or_b64 exec, exec, s[8:9]
	v_lshl_add_u64 v[0:1], v[0:1], 0, v[50:51]
	global_load_dwordx4 v[28:31], v[0:1], off
	global_load_dwordx4 v[24:27], v[0:1], off offset:1024
	global_load_dwordx4 v[20:23], v[0:1], off offset:2048
	global_load_dwordx4 v[16:19], v[0:1], off offset:3072
	s_movk_i32 s6, 0x1000
	v_add_co_u32_e32 v0, vcc, s6, v0
	v_lshlrev_b64 v[64:65], 12, v[2:3]
	s_nop 0
	v_addc_co_u32_e32 v1, vcc, 0, v1, vcc
	global_load_dwordx4 v[12:15], v[0:1], off
	global_load_dwordx4 v[120:123], v[0:1], off offset:1024
	global_load_dwordx4 v[124:127], v[0:1], off offset:2048
	global_load_dwordx4 v[128:131], v[0:1], off offset:3072
	s_mov_b32 s6, 0x800000
	v_min_i32_e32 v68, 0x4000, v32
	v_lshl_add_u64 v[32:33], v[32:33], 0, s[78:79]
	v_lshl_add_u64 v[48:49], v[48:49], 0, s[16:17]
	s_waitcnt vmcnt(4)
	v_mov_b32_e32 v4, v29
	s_waitcnt vmcnt(3)
	v_mov_b32_e32 v5, v25
	v_mov_b32_e32 v2, v28
	v_mov_b32_e32 v3, v24
	v_pk_mul_f32 v[4:5], v[4:5], v[4:5]
	v_mov_b32_e32 v6, v31
	v_mov_b32_e32 v7, v27
	v_pk_fma_f32 v[2:3], v[2:3], v[2:3], v[4:5]
	v_mov_b32_e32 v4, v30
	v_mov_b32_e32 v5, v26
	v_pk_mul_f32 v[6:7], v[6:7], v[6:7]
	s_nop 0
	v_pk_fma_f32 v[4:5], v[4:5], v[4:5], v[6:7]
	s_waitcnt vmcnt(2)
	v_pk_mul_f32 v[6:7], v[20:21], v[20:21]
	v_pk_add_f32 v[2:3], v[2:3], v[4:5]
	v_pk_mul_f32 v[4:5], v[22:23], v[22:23]
	v_pk_add_f32 v[2:3], v[2:3], v[2:3] op_sel:[0,1] op_sel_hi:[1,0]
	v_pk_mov_b32 v[8:9], v[6:7], v[4:5] op_sel:[1,0]
	v_mov_b32_e32 v7, v5
	v_pk_add_f32 v[4:5], v[8:9], v[6:7]
	s_waitcnt vmcnt(0)
	v_mul_f32_e32 v6, v12, v12
	v_mul_f32_e32 v7, v13, v13
	v_pk_add_f32 v[4:5], v[4:5], v[4:5] op_sel:[0,1] op_sel_hi:[1,0]
	v_mov_b32_e32 v3, v6
	v_mov_b32_e32 v5, v7
	v_pk_add_f32 v[2:3], v[2:3], v[4:5]
	v_mul_f32_e32 v4, v17, v17
	v_mul_f32_e32 v6, v19, v19
	v_mul_f32_e32 v8, v14, v14
	v_mul_f32_e32 v9, v15, v15
	v_pk_fma_f32 v[4:5], v[16:17], v[16:17], v[4:5] op_sel_hi:[1,1,0]
	v_pk_fma_f32 v[6:7], v[18:19], v[18:19], v[6:7] op_sel_hi:[1,1,0]
	v_mov_b32_e32 v5, v8
	v_mov_b32_e32 v7, v9
	v_mov_b32_e32 v8, v120
	v_mov_b32_e32 v9, v121
	v_mov_b32_e32 v10, v122
	v_mov_b32_e32 v11, v123
	v_pk_add_f32 v[4:5], v[4:5], v[6:7]
	s_nop 0
	v_pk_add_f32 v[60:61], v[2:3], v[4:5]
	s_waitcnt vmcnt(0)
	v_pk_mul_f32 v[2:3], v[10:11], v[10:11]
	v_pk_mul_f32 v[4:5], v[8:9], v[8:9]
	v_pk_add_f32 v[60:61], v[60:61], v[60:61] op_sel:[0,1] op_sel_hi:[1,0]
	v_pk_mov_b32 v[6:7], v[4:5], v[2:3] op_sel:[1,0]
	v_mov_b32_e32 v5, v3
	v_pk_add_f32 v[62:63], v[6:7], v[4:5]
	v_mov_b32_e32 v4, v124
	v_mov_b32_e32 v5, v125
	v_mov_b32_e32 v6, v126
	v_mov_b32_e32 v7, v127
	s_nop 0
	v_mov_b32_e32 v0, v128
	v_mov_b32_e32 v1, v129
	v_mov_b32_e32 v2, v130
	v_mov_b32_e32 v3, v131
	v_pk_add_f32 v[62:63], v[62:63], v[62:63] op_sel:[0,1] op_sel_hi:[1,0]
	global_load_dwordx4 v[78:81], v[36:37], off
	s_waitcnt vmcnt(1)
	v_mul_f32_e32 v34, v0, v0
	v_mul_f32_e32 v66, v1, v1
	v_mov_b32_e32 v61, v34
	v_mov_b32_e32 v63, v66
	v_mul_f32_e32 v34, v5, v5
	v_mul_f32_e32 v67, v2, v2
	v_pk_add_f32 v[60:61], v[60:61], v[62:63]
	v_pk_fma_f32 v[62:63], v[4:5], v[4:5], v[34:35] op_sel_hi:[1,1,0]
	v_mul_f32_e32 v34, v7, v7
	v_mul_f32_e32 v69, v3, v3
	v_mov_b32_e32 v63, v67
	v_pk_fma_f32 v[66:67], v[6:7], v[6:7], v[34:35] op_sel_hi:[1,1,0]
	s_nop 0
	v_mov_b32_e32 v67, v69
	v_pk_add_f32 v[62:63], v[62:63], v[66:67]
	s_nop 0
	v_pk_add_f32 v[60:61], v[60:61], v[62:63]
	s_nop 0
	v_add_f32_e32 v34, v60, v61
	ds_bpermute_b32 v61, v70, v34
	v_ashrrev_i32_e32 v60, 12, v68
	s_waitcnt lgkmcnt(0)
	v_add_f32_e32 v34, v34, v61
	ds_bpermute_b32 v61, v71, v34
	s_waitcnt lgkmcnt(0)
	v_add_f32_e32 v34, v34, v61
	ds_bpermute_b32 v61, v72, v34
	s_waitcnt lgkmcnt(0)
	v_add_f32_e32 v34, v34, v61
	ds_bpermute_b32 v61, v73, v34
	s_waitcnt lgkmcnt(0)
	v_add_f32_e32 v34, v34, v61
	ds_bpermute_b32 v61, v74, v34
	s_waitcnt lgkmcnt(0)
	v_add_f32_e32 v34, v34, v61
	ds_bpermute_b32 v61, v75, v34
	s_waitcnt lgkmcnt(0)
	v_add_f32_e32 v34, v34, v61
	v_fmamk_f32 v34, v34, 0x3a000000, v76
	v_cmp_gt_f32_e32 vcc, s6, v34
	v_mul_f32_e32 v61, 0x4b800000, v34
	s_movk_i32 s6, 0x43ff
	v_cndmask_b32_e32 v34, v34, v61, vcc
	v_rsq_f32_e32 v34, v34
	s_nop 0
	v_mul_f32_e32 v61, 0x45800000, v34
	v_cndmask_b32_e32 v34, v34, v61, vcc
	v_mul_hi_i32_i24_e32 v61, 0x3000, v60
	v_mul_i32_i24_e32 v60, 0x3000, v60
	v_lshlrev_b64 v[60:61], 2, v[60:61]
	v_lshl_add_u64 v[62:63], s[12:13], 0, v[60:61]
	v_lshl_add_u64 v[60:61], s[14:15], 0, v[60:61]
	v_lshl_add_u64 v[68:69], v[60:61], 0, v[50:51]
	v_lshl_add_u64 v[66:67], v[62:63], 0, v[50:51]
	global_load_dwordx4 v[86:89], v[68:69], off
	global_load_dwordx4 v[82:85], v[66:67], off
	global_load_dwordx4 v[120:123], v[36:37], off offset:1024
	global_load_dwordx4 v[124:127], v[66:67], off offset:1024
	global_load_dwordx4 v[128:131], v[68:69], off offset:1024
	global_load_dwordx4 v[132:135], v[36:37], off offset:2048
	global_load_dwordx4 v[136:139], v[66:67], off offset:2048
	global_load_dwordx4 v[140:143], v[68:69], off offset:2048
	global_load_dwordx4 v[144:147], v[36:37], off offset:3072
	global_load_dwordx4 v[148:151], v[66:67], off offset:3072
	global_load_dwordx4 v[152:155], v[68:69], off offset:3072
	v_pk_mul_f32 v[30:31], v[30:31], v[34:35] op_sel_hi:[1,0]
	v_pk_mul_f32 v[28:29], v[28:29], v[34:35] op_sel_hi:[1,0]
	s_waitcnt vmcnt(2)
; __device__ __forceinline__ unsigned pk2(float lo, float hi) { return f2bf(lo) | (f2bf(hi) << 16); }
; #define c opq(blockIdx.x)
; __device__ __forceinline__ void phase_norm_mod(const float* srcL, const float* srcC, const float* g, const float* mod_sh, const float* mod_sc, bf16_t* dst, int nrows, const float* part = nullptr, const float* pgate = nullptr, const bf16_t* srcLb = nullptr) {
;     ...
;         for (int j = 0; j < 8; ++j) { const int c = j * 256 + lane * 4; const f32x4 gv = *(const f32x4*)(g + c), shv = *(const f32x4*)(sh + c), scv = *(const f32x4*)(sc + c);
;             const f32x4 y = (v[j] * rstd) * gv; const f32x4 h = y * (scv + 1.f) + shv;
;             u32x2 o; o.x = pk2(h.x, h.y); o.y = pk2(h.z, h.w); *(u32x2*)(dst + (size_t)row * DM + c) = o; }
	v_pk_mul_f32 v[30:31], v[80:81], v[30:31]
	v_pk_mul_f32 v[28:29], v[78:79], v[28:29]
	v_pk_mul_f32 v[24:25], v[24:25], v[34:35] op_sel_hi:[1,0]
	v_pk_mul_f32 v[26:27], v[26:27], v[34:35] op_sel_hi:[1,0]
	v_pk_mul_f32 v[22:23], v[22:23], v[34:35] op_sel_hi:[1,0]
	v_pk_mul_f32 v[20:21], v[20:21], v[34:35] op_sel_hi:[1,0]
	v_pk_mul_f32 v[18:19], v[18:19], v[34:35] op_sel_hi:[1,0]
	v_pk_mul_f32 v[16:17], v[16:17], v[34:35] op_sel_hi:[1,0]
	v_pk_mul_f32 v[14:15], v[14:15], v[34:35] op_sel_hi:[1,0]
	v_pk_mul_f32 v[12:13], v[12:13], v[34:35] op_sel_hi:[1,0]
	v_pk_mul_f32 v[10:11], v[10:11], v[34:35] op_sel_hi:[1,0]
	v_pk_mul_f32 v[8:9], v[8:9], v[34:35] op_sel_hi:[1,0]
	v_pk_mul_f32 v[6:7], v[6:7], v[34:35] op_sel_hi:[1,0]
	v_pk_mul_f32 v[4:5], v[4:5], v[34:35] op_sel_hi:[1,0]
	v_pk_mul_f32 v[2:3], v[2:3], v[34:35] op_sel_hi:[1,0]
	v_pk_mul_f32 v[0:1], v[0:1], v[34:35] op_sel_hi:[1,0]
	v_cmp_lt_i32_e32 vcc, s6, v32
	s_or_b64 s[18:19], vcc, s[18:19]
	s_waitcnt vmcnt(1)
	v_pk_add_f32 v[80:81], v[86:87], 1.0 op_sel_hi:[1,0]
	v_pk_add_f32 v[78:79], v[88:89], 1.0 op_sel_hi:[1,0]
	s_waitcnt vmcnt(0)
	v_pk_fma_f32 v[28:29], v[80:81], v[28:29], v[82:83]
	v_pk_fma_f32 v[78:79], v[78:79], v[30:31], v[84:85]
	v_bfe_u32 v30, v28, 16, 1
	v_add3_u32 v28, v28, v30, s0
	v_bfe_u32 v30, v29, 16, 1
	v_lshrrev_b32_e32 v28, 16, v28
	v_add3_u32 v29, v29, v30, s0
	v_and_or_b32 v30, v29, s1, v28
	v_bfe_u32 v28, v78, 16, 1
	v_add3_u32 v28, v78, v28, s0
	v_bfe_u32 v29, v79, 16, 1
	v_lshrrev_b32_e32 v28, 16, v28
	v_add3_u32 v29, v79, v29, s0
	v_and_or_b32 v31, v29, s1, v28
	v_lshl_add_u64 v[28:29], v[46:47], 0, v[64:65]
	global_store_dwordx2 v[28:29], v[30:31], off
	v_mov_b32_e32 v78, v120
	v_mov_b32_e32 v79, v121
	v_mov_b32_e32 v80, v122
	v_mov_b32_e32 v81, v123
	v_mov_b32_e32 v82, v124
	v_mov_b32_e32 v83, v125
	v_mov_b32_e32 v84, v126
	v_mov_b32_e32 v85, v127
	v_mov_b32_e32 v86, v128
	v_mov_b32_e32 v87, v129
	v_mov_b32_e32 v88, v130
	v_mov_b32_e32 v89, v131
	v_pk_mul_f32 v[24:25], v[78:79], v[24:25]
	v_pk_mul_f32 v[26:27], v[80:81], v[26:27]
	v_pk_add_f32 v[64:65], v[86:87], 1.0 op_sel_hi:[1,0]
	v_pk_add_f32 v[30:31], v[88:89], 1.0 op_sel_hi:[1,0]
	v_pk_fma_f32 v[24:25], v[64:65], v[24:25], v[82:83]
	v_pk_fma_f32 v[26:27], v[30:31], v[26:27], v[84:85]
	v_bfe_u32 v30, v24, 16, 1
	v_add3_u32 v24, v24, v30, s0
	v_bfe_u32 v30, v25, 16, 1
	v_lshrrev_b32_e32 v24, 16, v24
	v_add3_u32 v25, v25, v30, s0
	v_and_or_b32 v24, v25, s1, v24
	v_bfe_u32 v25, v26, 16, 1
	v_add3_u32 v25, v26, v25, s0
	v_bfe_u32 v26, v27, 16, 1
	v_lshrrev_b32_e32 v25, 16, v25
	v_add3_u32 v26, v27, v26, s0
	v_and_or_b32 v25, v26, s1, v25
	global_store_dwordx2 v[28:29], v[24:25], off offset:512
	v_mov_b32_e32 v24, v132
	v_mov_b32_e32 v25, v133
	v_mov_b32_e32 v26, v134
	v_mov_b32_e32 v27, v135
	s_nop 0
	v_mov_b32_e32 v78, v136
	v_mov_b32_e32 v79, v137
	v_mov_b32_e32 v80, v138
	v_mov_b32_e32 v81, v139
	v_mov_b32_e32 v82, v140
	v_mov_b32_e32 v83, v141
	v_mov_b32_e32 v84, v142
	v_mov_b32_e32 v85, v143
	v_pk_mul_f32 v[20:21], v[24:25], v[20:21]
	v_pk_mul_f32 v[22:23], v[26:27], v[22:23]
	v_pk_add_f32 v[26:27], v[82:83], 1.0 op_sel_hi:[1,0]
	v_pk_add_f32 v[24:25], v[84:85], 1.0 op_sel_hi:[1,0]
	v_pk_fma_f32 v[20:21], v[26:27], v[20:21], v[78:79]
	v_pk_fma_f32 v[22:23], v[24:25], v[22:23], v[80:81]
	v_bfe_u32 v24, v20, 16, 1
	v_add3_u32 v20, v20, v24, s0
	v_bfe_u32 v24, v21, 16, 1
	v_lshrrev_b32_e32 v20, 16, v20
	v_add3_u32 v21, v21, v24, s0
	v_and_or_b32 v20, v21, s1, v20
	v_bfe_u32 v21, v22, 16, 1
	v_add3_u32 v21, v22, v21, s0
	v_bfe_u32 v22, v23, 16, 1
	v_lshrrev_b32_e32 v21, 16, v21
	v_add3_u32 v22, v23, v22, s0
	v_and_or_b32 v21, v22, s1, v21
	global_store_dwordx2 v[28:29], v[20:21], off offset:1024
	v_mov_b32_e32 v20, v144
	v_mov_b32_e32 v21, v145
	v_mov_b32_e32 v22, v146
	v_mov_b32_e32 v23, v147
	s_nop 0
	v_mov_b32_e32 v24, v148
	v_mov_b32_e32 v25, v149
	v_mov_b32_e32 v26, v150
	v_mov_b32_e32 v27, v151
	s_nop 0
	v_mov_b32_e32 v64, v152
	v_mov_b32_e32 v65, v153
	v_mov_b32_e32 v66, v154
	v_mov_b32_e32 v67, v155
	v_pk_mul_f32 v[16:17], v[20:21], v[16:17]
	v_pk_mul_f32 v[18:19], v[22:23], v[18:19]
	v_pk_add_f32 v[22:23], v[64:65], 1.0 op_sel_hi:[1,0]
	v_pk_add_f32 v[20:21], v[66:67], 1.0 op_sel_hi:[1,0]
	v_pk_fma_f32 v[16:17], v[16:17], v[22:23], v[24:25]
	v_pk_fma_f32 v[18:19], v[18:19], v[20:21], v[26:27]
	v_bfe_u32 v20, v16, 16, 1
	v_add3_u32 v16, v16, v20, s0
	v_bfe_u32 v20, v17, 16, 1
	v_lshrrev_b32_e32 v16, 16, v16
	v_add3_u32 v17, v17, v20, s0
	v_and_or_b32 v16, v17, s1, v16
	v_bfe_u32 v17, v18, 16, 1
	v_add3_u32 v17, v18, v17, s0
	v_bfe_u32 v18, v19, 16, 1
	v_lshrrev_b32_e32 v17, 16, v17
	v_add3_u32 v18, v19, v18, s0
	v_and_or_b32 v17, v18, s1, v17
	global_store_dwordx2 v[28:29], v[16:17], off offset:1536
	v_lshl_add_u64 v[24:25], v[60:61], 0, v[52:53]
	global_load_dwordx4 v[16:19], v[38:39], off
	v_lshl_add_u64 v[20:21], v[62:63], 0, v[52:53]
	global_load_dwordx4 v[24:27], v[24:25], off
	s_waitcnt vmcnt(1)
; __device__ __forceinline__ unsigned pk2(float lo, float hi) { return f2bf(lo) | (f2bf(hi) << 16); }
; #define c opq(blockIdx.x)
; __device__ __forceinline__ void phase_norm_mod(const float* srcL, const float* srcC, const float* g, const float* mod_sh, const float* mod_sc, bf16_t* dst, int nrows, const float* part = nullptr, const float* pgate = nullptr, const bf16_t* srcLb = nullptr) {
;     ...
;         const float* sh = mod_sh + (size_t)ridx * 12288; const float* sc = mod_sc + (size_t)ridx * 12288;
; #pragma unroll
;         for (int j = 0; j < 8; ++j) { const int c = j * 256 + lane * 4; const f32x4 gv = *(const f32x4*)(g + c), shv = *(const f32x4*)(sh + c), scv = *(const f32x4*)(sc + c);
;             const f32x4 y = (v[j] * rstd) * gv; const f32x4 h = y * (scv + 1.f) + shv;
;             u32x2 o; o.x = pk2(h.x, h.y); o.y = pk2(h.z, h.w); *(u32x2*)(dst + (size_t)row * DM + c) = o; }
	v_pk_mul_f32 v[12:13], v[12:13], v[16:17]
	global_load_dwordx4 v[20:23], v[20:21], off
	v_pk_mul_f32 v[14:15], v[14:15], v[18:19]
	s_waitcnt vmcnt(1)
	v_pk_add_f32 v[18:19], v[24:25], 1.0 op_sel_hi:[1,0]
	v_pk_add_f32 v[16:17], v[26:27], 1.0 op_sel_hi:[1,0]
	s_waitcnt vmcnt(0)
	v_pk_fma_f32 v[12:13], v[12:13], v[18:19], v[20:21]
	v_pk_fma_f32 v[14:15], v[14:15], v[16:17], v[22:23]
	v_bfe_u32 v16, v12, 16, 1
	v_add3_u32 v12, v12, v16, s0
	v_bfe_u32 v16, v13, 16, 1
	v_lshrrev_b32_e32 v12, 16, v12
	v_add3_u32 v13, v13, v16, s0
	v_and_or_b32 v12, v13, s1, v12
	v_bfe_u32 v13, v14, 16, 1
	v_add3_u32 v13, v14, v13, s0
	v_bfe_u32 v14, v15, 16, 1
	v_lshrrev_b32_e32 v13, 16, v13
	v_add3_u32 v14, v15, v14, s0
	v_and_or_b32 v13, v14, s1, v13
	global_store_dwordx2 v[28:29], v[12:13], off offset:2048
	v_lshl_add_u64 v[20:21], v[60:61], 0, v[54:55]
	global_load_dwordx4 v[12:15], v[40:41], off
	v_lshl_add_u64 v[16:17], v[62:63], 0, v[54:55]
	global_load_dwordx4 v[20:23], v[20:21], off
	s_waitcnt vmcnt(1)
	v_pk_mul_f32 v[8:9], v[8:9], v[12:13]
	global_load_dwordx4 v[16:19], v[16:17], off
	v_pk_mul_f32 v[10:11], v[10:11], v[14:15]
	s_waitcnt vmcnt(1)
	v_pk_add_f32 v[14:15], v[20:21], 1.0 op_sel_hi:[1,0]
	v_pk_add_f32 v[12:13], v[22:23], 1.0 op_sel_hi:[1,0]
	s_waitcnt vmcnt(0)
	v_pk_fma_f32 v[8:9], v[8:9], v[14:15], v[16:17]
	v_pk_fma_f32 v[10:11], v[10:11], v[12:13], v[18:19]
	v_bfe_u32 v12, v8, 16, 1
	v_add3_u32 v8, v8, v12, s0
	v_bfe_u32 v12, v9, 16, 1
	v_lshrrev_b32_e32 v8, 16, v8
	v_add3_u32 v9, v9, v12, s0
	v_and_or_b32 v8, v9, s1, v8
	v_bfe_u32 v9, v10, 16, 1
	v_add3_u32 v9, v10, v9, s0
	v_bfe_u32 v10, v11, 16, 1
	v_lshrrev_b32_e32 v9, 16, v9
	v_add3_u32 v10, v11, v10, s0
	v_and_or_b32 v9, v10, s1, v9
	global_store_dwordx2 v[28:29], v[8:9], off offset:2560
	v_lshl_add_u64 v[16:17], v[60:61], 0, v[56:57]
	global_load_dwordx4 v[8:11], v[42:43], off
	v_lshl_add_u64 v[12:13], v[62:63], 0, v[56:57]
	global_load_dwordx4 v[16:19], v[16:17], off
	s_waitcnt vmcnt(1)
	v_pk_mul_f32 v[4:5], v[4:5], v[8:9]
	global_load_dwordx4 v[12:15], v[12:13], off
	v_pk_mul_f32 v[6:7], v[6:7], v[10:11]
	s_waitcnt vmcnt(1)
	v_pk_add_f32 v[10:11], v[16:17], 1.0 op_sel_hi:[1,0]
	v_pk_add_f32 v[8:9], v[18:19], 1.0 op_sel_hi:[1,0]
	s_waitcnt vmcnt(0)
	v_pk_fma_f32 v[4:5], v[4:5], v[10:11], v[12:13]
	v_pk_fma_f32 v[6:7], v[6:7], v[8:9], v[14:15]
	v_bfe_u32 v8, v4, 16, 1
	v_add3_u32 v4, v4, v8, s0
	v_bfe_u32 v8, v5, 16, 1
	v_lshrrev_b32_e32 v4, 16, v4
	v_add3_u32 v5, v5, v8, s0
	v_and_or_b32 v4, v5, s1, v4
	v_bfe_u32 v5, v6, 16, 1
	v_add3_u32 v5, v6, v5, s0
	v_bfe_u32 v6, v7, 16, 1
	v_lshrrev_b32_e32 v5, 16, v5
	v_add3_u32 v6, v7, v6, s0
	v_and_or_b32 v5, v6, s1, v5
	global_store_dwordx2 v[28:29], v[4:5], off offset:3072
	v_lshl_add_u64 v[12:13], v[60:61], 0, v[58:59]
	global_load_dwordx4 v[4:7], v[44:45], off
	v_lshl_add_u64 v[8:9], v[62:63], 0, v[58:59]
	global_load_dwordx4 v[12:15], v[12:13], off
	s_waitcnt vmcnt(1)
	v_pk_mul_f32 v[0:1], v[0:1], v[4:5]
	global_load_dwordx4 v[8:11], v[8:9], off
	v_pk_mul_f32 v[2:3], v[2:3], v[6:7]
	s_waitcnt vmcnt(1)
	v_pk_add_f32 v[6:7], v[12:13], 1.0 op_sel_hi:[1,0]
	v_pk_add_f32 v[4:5], v[14:15], 1.0 op_sel_hi:[1,0]
	s_waitcnt vmcnt(0)
	v_pk_fma_f32 v[0:1], v[0:1], v[6:7], v[8:9]
	v_pk_fma_f32 v[2:3], v[2:3], v[4:5], v[10:11]
	v_bfe_u32 v4, v0, 16, 1
	v_add3_u32 v0, v0, v4, s0
	v_bfe_u32 v4, v1, 16, 1
	v_lshrrev_b32_e32 v0, 16, v0
	v_add3_u32 v1, v1, v4, s0
	v_and_or_b32 v0, v1, s1, v0
	v_bfe_u32 v1, v2, 16, 1
	v_add3_u32 v1, v2, v1, s0
	v_bfe_u32 v2, v3, 16, 1
	v_lshrrev_b32_e32 v1, 16, v1
	v_add3_u32 v2, v3, v2, s0
	v_and_or_b32 v1, v2, s1, v1
	global_store_dwordx2 v[28:29], v[0:1], off offset:3584
	s_andn2_b64 exec, exec, s[18:19]
	s_cbranch_execz .LBB0_140
